# s1 head loop and ssd_sample head loop: counted waits leave stores in flight, dsk load pipelined one head ahead
# speedup vs baseline: 1.0567x; 1.0013x over previous
.LBB0_260:
	s_or_b64 exec, exec, s[0:1]
	v_writelane_b32 v241, s78, 29
	v_readlane_b32 s4, v242, 2
	v_mov_b32_e32 v75, v2
	v_cndmask_b32_e64 v86, 0, 1, s[78:79]
	v_lshlrev_b32_e32 v74, 5, v86
	v_readlane_b32 s16, v242, 14
	v_readlane_b32 s17, v242, 15
	s_lshr_b32 s0, s97, 1
	s_and_b32 s0, s0, 15
	v_lshl_add_u64 v[148:149], s[16:17], 0, v[74:75]
	v_lshrrev_b32_e32 v74, 2, v66
	v_and_b32_e32 v88, 12, v74
	v_lshlrev_b32_e32 v74, 5, v78
	s_lshl_b32 s1, s0, 4
	s_lshl_b32 s54, s0, 7
	v_or_b32_e32 v89, v74, v67
	v_or_b32_e32 v90, v74, v88
	v_lshlrev_b32_e32 v74, 5, v134
	v_readlane_b32 s5, v242, 3
	v_readlane_b32 s6, v242, 4
	v_readlane_b32 s7, v242, 5
	v_readlane_b32 s8, v242, 6
	v_readlane_b32 s9, v242, 7
	v_readlane_b32 s10, v242, 8
	v_readlane_b32 s11, v242, 9
	v_readlane_b32 s12, v242, 10
	v_readlane_b32 s13, v242, 11
	v_readlane_b32 s14, v242, 12
	v_readlane_b32 s15, v242, 13
	v_and_b32_e32 v92, 0x60, v74
	v_mul_u32_u24_e32 v74, 0x88, v82
	s_add_u32 s2, s58, s1
	v_lshlrev_b32_e32 v4, 3, v86
	v_mov_b32_e32 v5, v2
	v_cmp_lt_i32_e64 s[4:5], 2, v73
	v_cmp_lt_i32_e64 s[6:7], 1, v73
	v_cmp_lt_i32_e64 s[8:9], 0, v73
	v_cmp_lt_i32_e64 s[10:11], -1, v73
	v_cmp_lt_i32_e64 s[12:13], -2, v73
	v_cmp_lt_i32_e64 s[14:15], -3, v73
	v_cmp_lt_i32_e64 s[16:17], -4, v73
	v_lshlrev_b32_e32 v73, 1, v72
	v_or_b32_e32 v75, v81, v88
	v_lshlrev_b32_e32 v74, 1, v74
	s_addc_u32 s3, s59, 0
	v_or_b32_e32 v3, 16, v68
	v_add3_u32 v168, 0, v73, v74
	v_add_u32_e32 v74, 0, v69
	v_or_b32_e32 v69, 2, v75
	v_or_b32_e32 v81, 16, v75
	v_lshl_add_u64 v[4:5], s[2:3], 0, v[4:5]
	s_add_u32 s2, s56, s54
	v_add3_u32 v80, v80, v67, 16
	v_cmp_gt_i32_e64 s[22:23], v69, v68
	v_or_b32_e32 v73, 3, v75
	v_cmp_gt_i32_e64 s[26:27], v81, v68
	s_addc_u32 s3, s57, 0
	v_cmp_gt_i32_e64 s[56:57], v69, v3
	v_ashrrev_i32_e32 v69, 31, v68
	v_ashrrev_i32_e32 v81, 31, v80
	v_readlane_b32 s18, v242, 16
	v_readlane_b32 s19, v242, 17
	v_cmp_gt_i32_e64 s[24:25], v73, v68
	v_or_b32_e32 v95, 17, v75
	v_or_b32_e32 v96, 18, v75
	v_or_b32_e32 v97, 19, v75
	v_or_b32_e32 v98, 32, v75
	v_or_b32_e32 v99, 33, v75
	v_or_b32_e32 v100, 34, v75
	v_or_b32_e32 v101, 35, v75
	v_or_b32_e32 v102, 48, v75
	v_or_b32_e32 v103, 49, v75
	v_or_b32_e32 v104, 50, v75
	v_or_b32_e32 v105, 51, v75
	v_lshl_add_u64 v[84:85], s[2:3], 0, v[68:69]
	v_lshl_add_u64 v[80:81], s[2:3], 0, v[80:81]
	v_cmp_gt_i32_e64 s[58:59], v73, v3
	v_mul_u32_u24_e32 v73, 0x88, v90
	s_movk_i32 s2, 0xfef2
	s_mov_b32 s95, s52
	v_add_u32_e32 v94, s52, v79
	v_cmp_gt_i32_e64 s[18:19], v75, v68
	v_cmp_lt_i32_e64 s[20:21], v75, v68
	v_lshl_add_u32 v169, v75, 1, v74
	v_cmp_gt_i32_e64 s[28:29], v95, v68
	v_cmp_gt_i32_e64 s[30:31], v96, v68
	v_cmp_gt_i32_e64 s[34:35], v97, v68
	v_cmp_gt_i32_e64 s[36:37], v98, v68
	v_cmp_gt_i32_e64 s[38:39], v99, v68
	v_cmp_gt_i32_e64 s[40:41], v100, v68
	v_cmp_gt_i32_e64 s[42:43], v101, v68
	v_cmp_gt_i32_e64 s[44:45], v102, v68
	v_cmp_gt_i32_e64 s[46:47], v103, v68
	v_cmp_gt_i32_e64 s[48:49], v104, v68
	v_cmp_gt_i32_e64 s[50:51], v105, v68
	v_cmp_gt_i32_e64 s[52:53], v75, v3
	v_cmp_lt_i32_e64 s[0:1], v75, v3
	v_mad_u64_u32 v[74:75], s[2:3], v68, s2, v[74:75]
	v_lshlrev_b32_e32 v73, 1, v73
	v_lshlrev_b32_e32 v68, 1, v68
	v_ashrrev_i32_e32 v83, 8, v66
	v_add_u32_e32 v171, v74, v73
	v_add3_u32 v172, 0, v73, v68
	v_add_u32_e32 v73, 0x1100, v73
	v_and_b32_e32 v66, 7, v66
	v_add_u32_e32 v173, v74, v73
	v_lshlrev_b32_e32 v74, 7, v67
	v_lshlrev_b32_e32 v178, 5, v66
	v_or_b32_e32 v66, v92, v88
	v_lshl_or_b32 v91, v83, 5, v67
	v_or_b32_e32 v93, v92, v67
	v_lshlrev_b32_e32 v67, 2, v67
	v_lshlrev_b32_e32 v150, 2, v66
	v_lshlrev_b64 v[4:5], 15, v[4:5]
	v_lshl_or_b32 v66, v83, 12, v74
	v_lshl_or_b32 v176, v76, 7, v67
	v_ashrrev_i32_e32 v67, 31, v66
	v_lshl_add_u64 v[4:5], s[74:75], 0, v[4:5]
	v_lshl_add_u64 v[154:155], v[66:67], 2, v[4:5]
	v_lshl_add_u32 v4, v86, 9, v82
	v_mov_b32_e32 v5, v2
	v_lshlrev_b64 v[4:5], 1, v[4:5]
	v_mad_u64_u32 v[4:5], s[2:3], v70, s68, v[4:5]
	v_mov_b32_e32 v66, v5
	v_mad_u64_u32 v[66:67], s[2:3], v71, s68, v[66:67]
	v_mov_b32_e32 v5, v66
	v_lshlrev_b32_e32 v87, 10, v86
	v_lshl_add_u64 v[156:157], s[76:77], 0, v[4:5]
	v_lshlrev_b64 v[4:5], 11, v[84:85]
	v_lshlrev_b32_e32 v66, 1, v90
	v_or3_b32 v4, v4, v87, v66
	v_lshl_add_u64 v[158:159], s[76:77], 0, v[4:5]
	v_lshlrev_b64 v[4:5], 11, v[80:81]
	v_mul_u32_u24_e32 v69, 0x110, v89
	v_add3_u32 v174, 0, v73, v68
	v_mul_u32_u24_e32 v68, 0x110, v93
	v_mul_lo_u32 v73, v91, s55
	v_or3_b32 v4, v4, v87, v66
	v_writelane_b32 v241, s79, 30
	v_add_u32_e32 v170, 0x1100, v169
	v_lshl_or_b32 v175, v78, 8, v79
	v_lshlrev_b32_e32 v177, 2, v72
	v_or_b32_e32 v152, 0x2040, v150
	v_mov_b32_e32 v153, v2
	v_lshl_add_u64 v[160:161], s[76:77], 0, v[4:5]
	v_mov_b32_e32 v151, v2
	s_mov_b32 s94, 0x199fc
	v_add_u32_e32 v179, v77, v69
	v_add_u32_e32 v180, v77, v73
	v_add_u32_e32 v181, v94, v68
	v_cmp_gt_i32_e64 s[60:61], v95, v3
	v_cmp_gt_i32_e64 s[62:63], v96, v3
	v_cmp_gt_i32_e64 s[64:65], v97, v3
	v_cmp_gt_i32_e64 s[66:67], v98, v3
	v_cmp_gt_i32_e64 s[68:69], v99, v3
	v_cmp_gt_i32_e64 s[70:71], v100, v3
	v_cmp_gt_i32_e64 s[72:73], v101, v3
	v_cmp_gt_i32_e64 s[74:75], v102, v3
	v_cmp_gt_i32_e64 s[76:77], v103, v3
	v_cmp_gt_i32_e64 s[78:79], v104, v3
	v_cmp_gt_i32_e64 s[80:81], v105, v3
	v_cmp_lt_i32_e64 s[82:83], -1, v76
	v_cmp_lt_i32_e64 s[84:85], 0, v76
	v_cmp_lt_i32_e64 s[86:87], 1, v76
	v_cmp_lt_i32_e64 s[88:89], 2, v76
	s_mov_b64 s[2:3], 0
	s_waitcnt vmcnt(0)
	s_branch .LBB0_262

.LBB0_262:
	global_load_dword v182, v[148:149], off
	s_and_saveexec_b64 s[92:93], s[90:91]
	s_cbranch_execz .LBB0_280
	v_add_u32_e32 v3, 0, v178
	v_add_u32_e32 v4, 0x1b800, v3
	v_add_u32_e32 v5, 0x1b810, v3
	ds_read_b128 v[118:121], v4
	ds_read_b128 v[98:101], v5
	v_add_u32_e32 v4, 0x1c000, v3
	v_add_u32_e32 v5, 0x1c010, v3
	ds_read_b128 v[122:125], v4
	ds_read_b128 v[102:105], v5
	v_add_u32_e32 v4, 0x1c800, v3
	v_add_u32_e32 v5, 0x1c810, v3
	ds_read_b128 v[126:129], v4
	ds_read_b128 v[106:109], v5
	v_add_u32_e32 v4, 0x1d000, v3
	v_add_u32_e32 v5, 0x1d010, v3
	ds_read_b128 v[130:133], v4
	ds_read_b128 v[110:113], v5
	v_add_u32_e32 v4, 0x1d800, v3
	v_add_u32_e32 v3, 0x1d810, v3
	ds_read_b128 v[114:117], v4
	ds_read_b128 v[94:97], v3
	s_waitcnt vmcnt(9)
	v_mov_b64_e32 v[72:73], v[44:45]
	v_mov_b64_e32 v[68:69], v[40:41]
	v_mov_b64_e32 v[76:77], v[48:49]
	v_mov_b64_e32 v[80:81], v[52:53]
	v_mov_b64_e32 v[84:85], v[56:57]
	v_mov_b64_e32 v[88:89], v[60:61]
	v_mov_b64_e32 v[92:93], v[64:65]
	s_cmpk_eq_i32 s2, 0x380
	v_mov_b64_e32 v[70:71], v[42:43]
	v_mov_b64_e32 v[66:67], v[38:39]
	v_mov_b64_e32 v[74:75], v[46:47]
	v_mov_b64_e32 v[78:79], v[50:51]
	v_mov_b64_e32 v[82:83], v[54:55]
	v_mov_b64_e32 v[86:87], v[58:59]
	v_mov_b64_e32 v[90:91], v[62:63]
	s_cbranch_scc1 .LBB0_279
	v_mov_b32_e32 v68, v2
	v_mov_b32_e32 v69, v2
	v_mov_b32_e32 v66, v2
	v_mov_b32_e32 v67, v2
	v_mov_b64_e32 v[72:73], v[68:69]
	v_lshl_add_u64 v[134:135], v[156:157], 0, s[2:3]
	v_mov_b64_e32 v[70:71], v[66:67]
	s_and_saveexec_b64 s[54:55], s[4:5]
	s_cbranch_execz .LBB0_266
	v_add_co_u32_e32 v4, vcc, 0x3ed4000, v134
	s_nop 1
	v_addc_co_u32_e32 v5, vcc, 0, v135, vcc
	global_load_dwordx4 v[70:73], v[4:5], off offset:1152

.LBB0_310:
	s_or_b64 exec, exec, s[10:11]
	s_lshl_b32 s10, s14, 15
	s_lshl_b64 s[8:9], s[8:9], 19
	v_readlane_b32 s12, v242, 21
	s_or_b32 s10, s8, s10
	v_readlane_b32 s20, v242, 29
	v_readlane_b32 s36, v242, 2
	v_readlane_b32 s21, v242, 30
	s_add_u32 s10, s20, s10
	v_lshlrev_b32_e32 v50, 5, v20
	v_readlane_b32 s48, v242, 14
	v_readlane_b32 s49, v242, 15
	s_addc_u32 s11, s21, s9
	v_lshlrev_b64 v[22:23], 9, v[2:3]
	v_lshl_add_u64 v[54:55], s[48:49], 0, v[50:51]
	v_lshl_add_u64 v[2:3], s[10:11], 0, v[22:23]
	v_lshlrev_b32_e32 v50, 6, v21
	v_lshl_add_u64 v[2:3], v[2:3], 0, v[50:51]
	s_mov_b64 s[10:11], 0x8000
	v_lshl_add_u64 v[14:15], v[2:3], 0, s[10:11]
	s_mov_b32 s10, 0x8000
	s_waitcnt lgkmcnt(0)
	s_barrier
	global_load_dwordx4 v[34:37], v[2:3], off offset:48
	global_load_dwordx4 v[38:41], v[2:3], off offset:32
	global_load_dwordx4 v[42:45], v[2:3], off offset:16
	global_load_dwordx4 v[46:49], v[2:3], off
	v_add_co_u32_e32 v2, vcc, s10, v2
	v_lshlrev_b32_e32 v19, 18, v20
	s_nop 0
	v_addc_co_u32_e32 v3, vcc, 0, v3, vcc
	global_load_dwordx4 v[10:13], v[2:3], off
	s_nop 0
	global_load_dwordx4 v[2:5], v[14:15], off offset:48
	global_load_dwordx4 v[6:9], v[14:15], off offset:32
	s_nop 0
	global_load_dwordx4 v[14:17], v[14:15], off offset:16
	v_lshl_add_u32 v53, v18, 2, 0
	v_or_b32_e32 v18, s8, v19
	v_mov_b32_e32 v19, s9
	v_lshl_add_u64 v[18:19], v[18:19], 0, v[22:23]
	v_readlane_b32 s13, v242, 22
	v_lshl_or_b32 v18, v21, 6, v18
	s_mov_b32 s12, 0
	v_add_u32_e32 v50, 0, v50
	v_cmp_eq_u32_e32 vcc, 0, v21
	v_lshl_add_u64 v[56:57], s[0:1], 0, v[18:19]
	v_lshl_add_u64 v[58:59], s[2:3], 0, v[18:19]
	s_add_i32 s13, 0, 0x3000
	s_mov_b64 s[8:9], 0
	v_readlane_b32 s37, v242, 3
	v_readlane_b32 s38, v242, 4
	v_readlane_b32 s39, v242, 5
	v_readlane_b32 s40, v242, 6
	v_readlane_b32 s41, v242, 7
	v_readlane_b32 s42, v242, 8
	v_readlane_b32 s43, v242, 9
	v_readlane_b32 s44, v242, 10
	v_readlane_b32 s45, v242, 11
	v_readlane_b32 s46, v242, 12
	v_readlane_b32 s47, v242, 13
	v_readlane_b32 s50, v242, 16
	v_readlane_b32 s51, v242, 17
	v_readlane_b32 s14, v242, 23
	v_readlane_b32 s15, v242, 24
	v_readlane_b32 s16, v242, 25
	v_readlane_b32 s17, v242, 26
	v_readlane_b32 s18, v242, 27
	v_readlane_b32 s19, v242, 28
	v_readlane_b32 s22, v242, 31
	v_readlane_b32 s23, v242, 32
	v_readlane_b32 s24, v242, 33
	v_readlane_b32 s25, v242, 34
	v_readlane_b32 s26, v242, 35
	v_readlane_b32 s27, v242, 36
	global_load_dword v200, v[54:55], off
	s_waitcnt vmcnt(0)
	s_branch .LBB0_312
.LBB0_311:
	s_or_b64 exec, exec, s[10:11]
	s_cmp_eq_u32 s8, 0x38000
	s_cbranch_scc1 .Lsmp_nodsk
	global_load_dword v200, v[54:55], off offset:4
.Lsmp_nodsk:
	s_add_i32 s12, s12, 1
	s_add_i32 s13, s13, 4
	v_lshl_add_u64 v[60:61], v[56:57], 0, s[8:9]
	s_add_u32 s8, s8, 0x8000
	global_store_dwordx4 v[60:61], v[34:37], off offset:-32
	global_store_dwordx4 v[60:61], v[38:41], off offset:-16
	global_store_dwordx4 v[60:61], v[42:45], off
	global_store_dwordx4 v[60:61], v[46:49], off offset:16
	s_addc_u32 s9, s9, 0
	v_mov_b64_e32 v[44:45], v[24:25]
	v_mov_b64_e32 v[48:49], v[28:29]
	v_mov_b64_e32 v[40:41], v[20:21]
	v_mov_b64_e32 v[36:37], v[32:33]
	v_add_u32_e32 v53, 0x100, v53
	v_lshl_add_u64 v[54:55], v[54:55], 0, 4
	s_cmp_eq_u32 s8, 0x40000
	v_mov_b64_e32 v[46:47], v[26:27]
	v_mov_b64_e32 v[42:43], v[22:23]
	v_mov_b64_e32 v[38:39], v[18:19]
	v_mov_b64_e32 v[34:35], v[30:31]
	s_cbranch_scc1 .LBB0_316
.LBB0_312:
	s_waitcnt vmcnt(5)
	v_mov_b64_e32 v[28:29], v[12:13]
	v_mov_b64_e32 v[24:25], v[16:17]
	v_mov_b64_e32 v[20:21], v[8:9]
	v_mov_b64_e32 v[32:33], v[4:5]
	v_mov_b64_e32 v[26:27], v[10:11]
	v_mov_b64_e32 v[22:23], v[14:15]
	v_mov_b64_e32 v[18:19], v[6:7]
	s_cmp_gt_u32 s12, 5
	v_mov_b64_e32 v[30:31], v[2:3]
	s_cbranch_scc1 .LBB0_314
	v_lshl_add_u64 v[10:11], v[58:59], 0, s[8:9]
	global_load_dwordx4 v[2:5], v[10:11], off offset:16
	global_load_dwordx4 v[6:9], v[10:11], off
	global_load_dwordx4 v[14:17], v[10:11], off offset:-16
	s_nop 0
	global_load_dwordx4 v[10:13], v[10:11], off offset:-32
.LBB0_314:
	v_mov_b32_e32 v98, s13
	ds_read2st64_b32 v[60:61], v53 offset1:8
	ds_read2_b32 v[62:63], v98 offset1:8
	s_waitcnt lgkmcnt(4)
	ds_read_b128 v[76:79], v50 offset:8192
	s_waitcnt lgkmcnt(3)
	ds_read_b128 v[80:83], v50 offset:8208
	ds_read2_b32 v[96:97], v98 offset0:32 offset1:40
	ds_read_b128 v[84:87], v50 offset:8224
	ds_read_b128 v[88:91], v50 offset:8240
	ds_read_b128 v[92:95], v50 offset:10240
	s_waitcnt lgkmcnt(6)
	v_mul_f32_e32 v62, v60, v62
	s_waitcnt lgkmcnt(5)
	v_pk_mul_f32 v[78:79], v[78:79], v[62:63] op_sel_hi:[1,0]
	v_pk_mul_f32 v[76:77], v[76:77], v[62:63] op_sel_hi:[1,0]
	s_waitcnt lgkmcnt(3)
	v_pk_fma_f32 v[78:79], v[48:49], v[96:97], v[78:79] op_sel_hi:[1,0,1]
	v_pk_fma_f32 v[76:77], v[46:47], v[96:97], v[76:77] op_sel_hi:[1,0,1]
	ds_read_b128 v[46:49], v50 offset:10256
	v_pk_mul_f32 v[80:81], v[62:63], v[80:81] op_sel_hi:[0,1]
	s_waitcnt lgkmcnt(1)
	v_mul_f32_e32 v93, v93, v77
	v_pk_fma_f32 v[80:81], v[42:43], v[96:97], v[80:81] op_sel_hi:[1,0,1]
	v_fmac_f32_e32 v93, v92, v76
	v_pk_mul_f32 v[82:83], v[62:63], v[82:83] op_sel_hi:[0,1]
	s_waitcnt lgkmcnt(0)
	v_mul_f32_e32 v42, v47, v81
	v_fmac_f32_e32 v93, v94, v78
	v_pk_fma_f32 v[82:83], v[44:45], v[96:97], v[82:83] op_sel_hi:[1,0,1]
	v_fmac_f32_e32 v42, v46, v80
	v_fmac_f32_e32 v93, v95, v79
	v_fmac_f32_e32 v42, v48, v82
	v_add_f32_e32 v92, 0, v93
	v_fmac_f32_e32 v42, v49, v83
	v_add_f32_e32 v92, v42, v92
	ds_read_b128 v[42:45], v50 offset:10272
	v_pk_mul_f32 v[48:49], v[62:63], v[84:85] op_sel_hi:[0,1]
	v_pk_mul_f32 v[46:47], v[62:63], v[86:87] op_sel_hi:[0,1]
	v_pk_fma_f32 v[48:49], v[38:39], v[96:97], v[48:49] op_sel_hi:[1,0,1]
	v_pk_fma_f32 v[46:47], v[40:41], v[96:97], v[46:47] op_sel_hi:[1,0,1]
	ds_read_b128 v[38:41], v50 offset:10288
	s_waitcnt lgkmcnt(1)
	v_mul_f32_e32 v43, v43, v49
	v_fmac_f32_e32 v43, v42, v48
	v_fmac_f32_e32 v43, v44, v46
	v_fmac_f32_e32 v43, v45, v47
	v_pk_mul_f32 v[44:45], v[62:63], v[88:89] op_sel_hi:[0,1]
	v_add_f32_e32 v92, v92, v43
	v_pk_mul_f32 v[42:43], v[62:63], v[90:91] op_sel_hi:[0,1]
	v_pk_fma_f32 v[86:87], v[34:35], v[96:97], v[44:45] op_sel_hi:[1,0,1]
	v_pk_fma_f32 v[84:85], v[36:37], v[96:97], v[42:43] op_sel_hi:[1,0,1]
	ds_read_b128 v[34:37], v50 offset:8704
	s_waitcnt lgkmcnt(1)
	v_mul_f32_e32 v39, v39, v87
	v_fmac_f32_e32 v39, v38, v86
	v_fmac_f32_e32 v39, v40, v84
	v_fmac_f32_e32 v39, v41, v85
	v_add_f32_e32 v96, v92, v39
	ds_read_b128 v[38:41], v50 offset:10752
	ds_read_b128 v[42:45], v50 offset:8720
	v_mul_f32_e32 v62, v61, v63
	s_waitcnt lgkmcnt(2)
	v_pk_mul_f32 v[34:35], v[34:35], v[62:63] op_sel_hi:[1,0]
	v_mov_b32_e32 v88, v97
	v_pk_fma_f32 v[76:77], v[76:77], v[88:89], v[34:35] op_sel_hi:[1,0,1]
	v_pk_mul_f32 v[36:37], v[36:37], v[62:63] op_sel_hi:[1,0]
	s_waitcnt lgkmcnt(1)
	v_mul_f32_e32 v39, v39, v77
	v_pk_fma_f32 v[78:79], v[78:79], v[88:89], v[36:37] op_sel_hi:[1,0,1]
	v_fmac_f32_e32 v39, v38, v76
	ds_read_b128 v[34:37], v50 offset:10768
	v_fmac_f32_e32 v39, v40, v78
	v_fmac_f32_e32 v39, v41, v79
	v_add_f32_e32 v63, 0, v39
	s_waitcnt lgkmcnt(1)
	v_pk_mul_f32 v[40:41], v[62:63], v[42:43] op_sel_hi:[0,1]
	v_pk_mul_f32 v[38:39], v[62:63], v[44:45] op_sel_hi:[0,1]
	v_pk_fma_f32 v[80:81], v[80:81], v[88:89], v[40:41] op_sel_hi:[1,0,1]
	v_pk_fma_f32 v[82:83], v[82:83], v[88:89], v[38:39] op_sel_hi:[1,0,1]
	ds_read_b128 v[38:41], v50 offset:8736
	s_waitcnt lgkmcnt(1)
	v_mul_f32_e32 v35, v35, v81
	v_fmac_f32_e32 v35, v34, v80
	v_fmac_f32_e32 v35, v36, v82
	v_fmac_f32_e32 v35, v37, v83
	v_add_f32_e32 v63, v35, v63
	ds_read_b128 v[34:37], v50 offset:10784
	ds_read_b128 v[42:45], v50 offset:8752
	s_waitcnt lgkmcnt(2)
	v_pk_mul_f32 v[38:39], v[62:63], v[38:39] op_sel_hi:[0,1]
	v_pk_mul_f32 v[40:41], v[62:63], v[40:41] op_sel_hi:[0,1]
	v_pk_fma_f32 v[48:49], v[48:49], v[88:89], v[38:39] op_sel_hi:[1,0,1]
	v_pk_fma_f32 v[46:47], v[46:47], v[88:89], v[40:41] op_sel_hi:[1,0,1]
	ds_read_b128 v[38:41], v50 offset:10800
	s_waitcnt lgkmcnt(2)
	v_mul_f32_e32 v35, v35, v49
	v_fmac_f32_e32 v35, v34, v48
	v_fmac_f32_e32 v35, v36, v46
	v_fmac_f32_e32 v35, v37, v47
	s_waitcnt lgkmcnt(1)
	v_pk_mul_f32 v[36:37], v[62:63], v[42:43] op_sel_hi:[0,1]
	v_add_f32_e32 v90, v63, v35
	v_pk_mul_f32 v[34:35], v[62:63], v[44:45] op_sel_hi:[0,1]
	v_pk_fma_f32 v[86:87], v[86:87], v[88:89], v[36:37] op_sel_hi:[1,0,1]
	v_pk_fma_f32 v[84:85], v[84:85], v[88:89], v[34:35] op_sel_hi:[1,0,1]
	s_waitcnt lgkmcnt(0)
	v_mul_f32_e32 v34, v39, v87
	v_fmac_f32_e32 v34, v38, v86
	v_fmac_f32_e32 v34, v40, v84
	ds_read2st64_b32 v[62:63], v53 offset0:16 offset1:24
	ds_read2_b32 v[88:89], v98 offset0:16 offset1:24
	v_fmac_f32_e32 v34, v41, v85
	v_add_f32_e32 v97, v90, v34
	ds_read_b128 v[34:37], v50 offset:9216
	ds_read2_b32 v[90:91], v98 offset0:48 offset1:56
	ds_read_b128 v[38:41], v50 offset:11264
	ds_read_b128 v[42:45], v50 offset:9232
	s_waitcnt lgkmcnt(4)
	v_mul_f32_e32 v88, v62, v88
	s_waitcnt lgkmcnt(3)
	v_pk_mul_f32 v[34:35], v[34:35], v[88:89] op_sel_hi:[1,0]
	v_pk_mul_f32 v[36:37], v[36:37], v[88:89] op_sel_hi:[1,0]
	s_waitcnt lgkmcnt(2)
	v_pk_fma_f32 v[76:77], v[76:77], v[90:91], v[34:35] op_sel_hi:[1,0,1]
	v_pk_fma_f32 v[78:79], v[78:79], v[90:91], v[36:37] op_sel_hi:[1,0,1]
	ds_read_b128 v[34:37], v50 offset:11280
	s_waitcnt lgkmcnt(2)
	v_mul_f32_e32 v39, v39, v77
	v_fmac_f32_e32 v39, v38, v76
	v_fmac_f32_e32 v39, v40, v78
	v_fmac_f32_e32 v39, v41, v79
	s_waitcnt lgkmcnt(1)
	v_pk_mul_f32 v[40:41], v[88:89], v[42:43] op_sel_hi:[0,1]
	v_add_f32_e32 v92, 0, v39
	v_pk_mul_f32 v[38:39], v[88:89], v[44:45] op_sel_hi:[0,1]
	v_pk_fma_f32 v[80:81], v[80:81], v[90:91], v[40:41] op_sel_hi:[1,0,1]
	v_pk_fma_f32 v[82:83], v[82:83], v[90:91], v[38:39] op_sel_hi:[1,0,1]
	ds_read_b128 v[38:41], v50 offset:9248
	s_waitcnt lgkmcnt(1)
	v_mul_f32_e32 v35, v35, v81
	v_fmac_f32_e32 v35, v34, v80
	v_fmac_f32_e32 v35, v36, v82
	v_fmac_f32_e32 v35, v37, v83
	v_add_f32_e32 v98, v35, v92
	ds_read_b128 v[34:37], v50 offset:11296
	ds_read_b128 v[42:45], v50 offset:9264
	s_waitcnt lgkmcnt(2)
	v_pk_mul_f32 v[38:39], v[88:89], v[38:39] op_sel_hi:[0,1]
	v_pk_mul_f32 v[40:41], v[88:89], v[40:41] op_sel_hi:[0,1]
	v_pk_fma_f32 v[94:95], v[48:49], v[90:91], v[38:39] op_sel_hi:[1,0,1]
	v_pk_fma_f32 v[92:93], v[46:47], v[90:91], v[40:41] op_sel_hi:[1,0,1]
	ds_read_b128 v[38:41], v50 offset:11312
	s_waitcnt lgkmcnt(2)
	v_mul_f32_e32 v35, v35, v95
	v_fmac_f32_e32 v35, v34, v94
	v_fmac_f32_e32 v35, v36, v92
	v_fmac_f32_e32 v35, v37, v93
	s_waitcnt lgkmcnt(1)
	v_pk_mul_f32 v[36:37], v[88:89], v[42:43] op_sel_hi:[0,1]
	v_add_f32_e32 v46, v98, v35
	v_pk_mul_f32 v[34:35], v[88:89], v[44:45] op_sel_hi:[0,1]
	v_pk_fma_f32 v[86:87], v[86:87], v[90:91], v[36:37] op_sel_hi:[1,0,1]
	v_pk_fma_f32 v[84:85], v[84:85], v[90:91], v[34:35] op_sel_hi:[1,0,1]
	ds_read_b128 v[34:37], v50 offset:9728
	s_waitcnt lgkmcnt(1)
	v_mul_f32_e32 v39, v39, v87
	v_fmac_f32_e32 v39, v38, v86
	v_fmac_f32_e32 v39, v40, v84
	v_fmac_f32_e32 v39, v41, v85
	v_add_f32_e32 v98, v46, v39
	ds_read_b128 v[38:41], v50 offset:11776
	ds_read_b128 v[42:45], v50 offset:9744
	v_mul_f32_e32 v88, v63, v89
	s_waitcnt lgkmcnt(2)
	v_pk_mul_f32 v[34:35], v[34:35], v[88:89] op_sel_hi:[1,0]
	v_mov_b32_e32 v90, v91
	v_pk_fma_f32 v[34:35], v[76:77], v[90:91], v[34:35] op_sel_hi:[1,0,1]
	v_pk_mul_f32 v[36:37], v[36:37], v[88:89] op_sel_hi:[1,0]
	s_waitcnt lgkmcnt(1)
	v_mul_f32_e32 v39, v39, v35
	v_pk_fma_f32 v[36:37], v[78:79], v[90:91], v[36:37] op_sel_hi:[1,0,1]
	ds_read_b128 v[46:49], v50 offset:11792
	v_fmac_f32_e32 v39, v38, v34
	v_fmac_f32_e32 v39, v40, v36
	v_fmac_f32_e32 v39, v41, v37
	v_add_f32_e32 v76, 0, v39
	s_waitcnt lgkmcnt(1)
	v_pk_mul_f32 v[38:39], v[88:89], v[44:45] op_sel_hi:[0,1]
	v_pk_mul_f32 v[42:43], v[88:89], v[42:43] op_sel_hi:[0,1]
	v_pk_fma_f32 v[40:41], v[82:83], v[90:91], v[38:39] op_sel_hi:[1,0,1]
	v_pk_fma_f32 v[38:39], v[80:81], v[90:91], v[42:43] op_sel_hi:[1,0,1]
	ds_read_b128 v[42:45], v50 offset:9760
	s_waitcnt lgkmcnt(1)
	v_mul_f32_e32 v47, v47, v39
	v_fmac_f32_e32 v47, v46, v38
	v_fmac_f32_e32 v47, v48, v40
	v_fmac_f32_e32 v47, v49, v41
	v_add_f32_e32 v89, v47, v76
	ds_read_b128 v[46:49], v50 offset:11808
	ds_read_b128 v[76:79], v50 offset:9776
	s_waitcnt lgkmcnt(2)
	v_pk_mul_f32 v[42:43], v[88:89], v[42:43] op_sel_hi:[0,1]
	v_pk_fma_f32 v[42:43], v[94:95], v[90:91], v[42:43] op_sel_hi:[1,0,1]
	v_pk_mul_f32 v[44:45], v[88:89], v[44:45] op_sel_hi:[0,1]
	s_waitcnt lgkmcnt(1)
	v_mul_f32_e32 v47, v47, v43
	v_pk_fma_f32 v[44:45], v[92:93], v[90:91], v[44:45] op_sel_hi:[1,0,1]
	v_fmac_f32_e32 v47, v46, v42
	ds_read_b128 v[80:83], v50 offset:11824
	v_fmac_f32_e32 v47, v48, v44
	v_fmac_f32_e32 v47, v49, v45
	v_add_f32_e32 v89, v89, v47
	s_waitcnt lgkmcnt(1)
	v_pk_mul_f32 v[46:47], v[88:89], v[78:79] op_sel_hi:[0,1]
	v_pk_mul_f32 v[76:77], v[88:89], v[76:77] op_sel_hi:[0,1]
	v_pk_fma_f32 v[48:49], v[84:85], v[90:91], v[46:47] op_sel_hi:[1,0,1]
	v_pk_fma_f32 v[46:47], v[86:87], v[90:91], v[76:77] op_sel_hi:[1,0,1]
	ds_bpermute_b32 v77, v64, v96
	s_waitcnt lgkmcnt(1)
	v_mul_f32_e32 v76, v81, v47
	v_fmac_f32_e32 v76, v80, v46
	v_fmac_f32_e32 v76, v82, v48
	v_fmac_f32_e32 v76, v83, v49
	v_add_f32_e32 v76, v89, v76
	ds_bpermute_b32 v78, v64, v97
	ds_bpermute_b32 v79, v64, v98
	ds_bpermute_b32 v80, v64, v76
	s_waitcnt lgkmcnt(3)
	v_add_f32_e32 v77, v96, v77
	s_waitcnt lgkmcnt(2)
	v_add_f32_e32 v78, v97, v78
	s_waitcnt lgkmcnt(1)
	v_add_f32_e32 v79, v98, v79
	s_waitcnt lgkmcnt(0)
	v_add_f32_e32 v81, v76, v80
	ds_bpermute_b32 v76, v65, v77
	ds_bpermute_b32 v80, v65, v78
	ds_bpermute_b32 v82, v65, v79
	ds_bpermute_b32 v83, v65, v81
	s_waitcnt lgkmcnt(3)
	v_add_f32_e32 v76, v77, v76
	s_waitcnt lgkmcnt(2)
	v_add_f32_e32 v77, v78, v80
	s_waitcnt lgkmcnt(1)
	v_add_f32_e32 v80, v79, v82
	s_waitcnt lgkmcnt(0)
	v_add_f32_e32 v82, v81, v83
	ds_bpermute_b32 v78, v66, v76
	ds_bpermute_b32 v79, v66, v77
	ds_bpermute_b32 v81, v66, v80
	ds_bpermute_b32 v83, v66, v82
	s_and_saveexec_b64 s[10:11], vcc
	s_cbranch_execz .LBB0_311
	v_add_u32_e32 v86, 0x80, v53
	s_waitcnt lgkmcnt(0)
	v_add_f32_e32 v85, v82, v83
	ds_read2st64_b32 v[82:83], v86 offset0:81 offset1:89
	v_add_f32_e32 v87, v80, v81
	ds_read2st64_b32 v[80:81], v86 offset0:97 offset1:105
	v_add_f32_e32 v77, v77, v79
	v_add_f32_e32 v76, v76, v78
	s_waitcnt lgkmcnt(1)
	v_mul_f32_e32 v78, 0xbfb8aa3b, v82
	v_mul_f32_e32 v79, 0xbfb8aa3b, v83
	s_waitcnt lgkmcnt(0)
	v_mul_f32_e32 v86, 0xbfb8aa3b, v80
	v_mul_f32_e32 v88, 0xbfb8aa3b, v81
	v_exp_f32_e32 v78, v78
	v_exp_f32_e32 v79, v79
	v_exp_f32_e32 v86, v86
	v_exp_f32_e32 v88, v88
	v_add_f32_e32 v78, 1.0, v78
	v_add_f32_e32 v79, 1.0, v79
	v_add_f32_e32 v86, 1.0, v86
	v_add_f32_e32 v88, 1.0, v88
	v_rcp_f32_e32 v78, v78
	v_rcp_f32_e32 v79, v79
	v_rcp_f32_e32 v86, v86
	v_rcp_f32_e32 v88, v88
	v_mul_f32_e32 v78, v82, v78
	v_mul_f32_e32 v79, v83, v79
	v_mul_f32_e32 v80, v80, v86
	v_mul_f32_e32 v81, v81, v88
	s_waitcnt vmcnt(4)
	v_fmac_f32_e32 v76, v60, v200
	v_fmac_f32_e32 v77, v61, v200
	v_fmac_f32_e32 v87, v62, v200
	v_fmac_f32_e32 v85, v63, v200
	v_mul_f32_e32 v60, v76, v78
	v_mul_f32_e32 v61, v77, v79
	v_mul_f32_e32 v62, v87, v80
	v_mul_f32_e32 v63, v85, v81
	ds_write2st64_b32 v53, v60, v61 offset0:49 offset1:57
	ds_write2st64_b32 v53, v62, v63 offset0:65 offset1:73
	s_branch .LBB0_311
